# phase 2 up-projection: k_nope / v units run K = 128 (one K iteration) since the bf16 weight rows k >= 128 are structural zeros
# speedup vs baseline: 1.0238x; 1.0013x over previous
.LBB0_389:
	s_ashr_i32 s57, s56, 31
	v_mad_u64_u32 v[130:131], s[14:15], s56, v135, v[134:135]
	v_mad_u64_u32 v[132:133], s[14:15], s56, v195, v[134:135]
	v_mov_b32_e32 v2, 0
	s_lshl_b64 s[58:59], s[56:57], 7
	v_ashrrev_i32_e32 v131, 31, v130
	v_ashrrev_i32_e32 v133, 31, v132
	s_mov_b64 s[64:65], 0
	s_cmp_lg_u32 s90, 0
	s_cselect_b64 s[60:61], 0, -1
	s_cselect_b64 s[62:63], -1, 0
	v_mov_b32_e32 v3, v2
	v_mov_b32_e32 v4, v2
	v_mov_b32_e32 v5, v2
	v_mov_b32_e32 v6, v2
	v_mov_b32_e32 v7, v2
	v_mov_b32_e32 v8, v2
	v_mov_b32_e32 v9, v2
	v_mov_b32_e32 v10, v2
	v_mov_b32_e32 v11, v2
	v_mov_b32_e32 v12, v2
	v_mov_b32_e32 v13, v2
	v_mov_b32_e32 v18, v2
	v_mov_b32_e32 v19, v2
	v_mov_b32_e32 v20, v2
	v_mov_b32_e32 v21, v2
	v_mov_b32_e32 v26, v2
	v_mov_b32_e32 v27, v2
	v_mov_b32_e32 v28, v2
	v_mov_b32_e32 v29, v2
	v_mov_b32_e32 v34, v2
	v_mov_b32_e32 v35, v2
	v_mov_b32_e32 v36, v2
	v_mov_b32_e32 v37, v2
	v_mov_b32_e32 v42, v2
	v_mov_b32_e32 v43, v2
	v_mov_b32_e32 v44, v2
	v_mov_b32_e32 v45, v2
	v_mov_b32_e32 v50, v2
	v_mov_b32_e32 v51, v2
	v_mov_b32_e32 v52, v2
	v_mov_b32_e32 v53, v2
	v_mov_b32_e32 v14, v2
	v_mov_b32_e32 v15, v2
	v_mov_b32_e32 v16, v2
	v_mov_b32_e32 v17, v2
	v_mov_b32_e32 v22, v2
	v_mov_b32_e32 v23, v2
	v_mov_b32_e32 v24, v2
	v_mov_b32_e32 v25, v2
	v_mov_b32_e32 v30, v2
	v_mov_b32_e32 v31, v2
	v_mov_b32_e32 v32, v2
	v_mov_b32_e32 v33, v2
	v_mov_b32_e32 v38, v2
	v_mov_b32_e32 v39, v2
	v_mov_b32_e32 v40, v2
	v_mov_b32_e32 v41, v2
	v_mov_b32_e32 v46, v2
	v_mov_b32_e32 v47, v2
	v_mov_b32_e32 v48, v2
	v_mov_b32_e32 v49, v2
	v_mov_b32_e32 v54, v2
	v_mov_b32_e32 v55, v2
	v_mov_b32_e32 v56, v2
	v_mov_b32_e32 v57, v2
	v_mov_b32_e32 v58, v2
	v_mov_b32_e32 v59, v2
	v_mov_b32_e32 v60, v2
	v_mov_b32_e32 v61, v2
	v_mov_b32_e32 v62, v2
	v_mov_b32_e32 v63, v2
	v_mov_b32_e32 v64, v2
	v_mov_b32_e32 v65, v2
	v_mov_b32_e32 v66, v2
	v_mov_b32_e32 v67, v2
	v_mov_b32_e32 v68, v2
	v_mov_b32_e32 v69, v2
	v_mov_b32_e32 v70, v2
	v_mov_b32_e32 v71, v2
	v_mov_b32_e32 v72, v2
	v_mov_b32_e32 v73, v2
	v_mov_b32_e32 v74, v2
	v_mov_b32_e32 v75, v2
	v_mov_b32_e32 v76, v2
	v_mov_b32_e32 v77, v2
	v_mov_b32_e32 v78, v2
	v_mov_b32_e32 v79, v2
	v_mov_b32_e32 v80, v2
	v_mov_b32_e32 v81, v2
	v_mov_b32_e32 v90, v2
	v_mov_b32_e32 v91, v2
	v_mov_b32_e32 v92, v2
	v_mov_b32_e32 v93, v2
	v_mov_b32_e32 v94, v2
	v_mov_b32_e32 v95, v2
	v_mov_b32_e32 v96, v2
	v_mov_b32_e32 v97, v2
	v_mov_b32_e32 v106, v2
	v_mov_b32_e32 v107, v2
	v_mov_b32_e32 v108, v2
	v_mov_b32_e32 v109, v2
	v_mov_b32_e32 v110, v2
	v_mov_b32_e32 v111, v2
	v_mov_b32_e32 v112, v2
	v_mov_b32_e32 v113, v2
	v_mov_b32_e32 v82, v2
	v_mov_b32_e32 v83, v2
	v_mov_b32_e32 v84, v2
	v_mov_b32_e32 v85, v2
	v_mov_b32_e32 v86, v2
	v_mov_b32_e32 v87, v2
	v_mov_b32_e32 v88, v2
	v_mov_b32_e32 v89, v2
	v_mov_b32_e32 v98, v2
	v_mov_b32_e32 v99, v2
	v_mov_b32_e32 v100, v2
	v_mov_b32_e32 v101, v2
	v_mov_b32_e32 v102, v2
	v_mov_b32_e32 v103, v2
	v_mov_b32_e32 v104, v2
	v_mov_b32_e32 v105, v2
	v_mov_b32_e32 v114, v2
	v_mov_b32_e32 v115, v2
	v_mov_b32_e32 v116, v2
	v_mov_b32_e32 v117, v2
	v_mov_b32_e32 v118, v2
	v_mov_b32_e32 v119, v2
	v_mov_b32_e32 v120, v2
	v_mov_b32_e32 v121, v2
	v_mov_b32_e32 v122, v2
	v_mov_b32_e32 v123, v2
	v_mov_b32_e32 v124, v2
	v_mov_b32_e32 v125, v2
	v_mov_b32_e32 v126, v2
	v_mov_b32_e32 v127, v2
	v_mov_b32_e32 v128, v2
	v_mov_b32_e32 v129, v2
